# in-proj gate planes stored write-through (sc1) so they do not occupy L2 (on top of v24)
# baseline (speedup 1.0000x reference)
; __device__ __forceinline__ u32x4 pack8(const float (&v)[8]) { u32x4 w; w.x = pk2(v[0], v[1]); w.y = pk2(v[2], v[3]); w.z = pk2(v[4], v[5]); w.w = pk2(v[6], v[7]); return w; }
;     __device__ __forceinline__ bool operator()(Acc& acc, const Unit& u, int wr, int wc, int fr, int fq, const LAS float* rstab) const {
;     ...
;             if (colt >= C_G) {
;                 const int pl = (u.pn < 19) ? bj : 2, go = (u.pn < 19) ? (u.pn - 11) * HALF : colt - (C_G + 2048);
;                 bf16_t* p0 = Gt + (size_t)rowb * 3072 + pl * 1024 + go + cl;
;                 float bg[8];
;                 { const f32x4 b0 = gld<f32x4>(bgate + pl * 1024 + go + cl), b1 = gld<f32x4>(bgate + pl * 1024 + go + cl + 4);
; #pragma unroll
;                   for (int e = 0; e < 4; ++e) { bg[e] = -LOG2E * b0[e]; bg[4 + e] = -LOG2E * b1[e]; } }
; #pragma unroll
;                 for (int ai = 0; ai < 2; ++ai)
; #pragma unroll
;                     for (int m = 0; m < 4; ++m) {
;                         const float nrs = -LOG2E * rsp[ai * HALF + m * 16];
;                         float v[8];
; #pragma unroll
;                         for (int e = 0; e < 4; ++e) {
;                             v[e] = 1.0f + __builtin_amdgcn_exp2f(fminf(__builtin_fmaf(acc[ai][bj][m][0][e], nrs, bg[e]), 86.f));
;                             v[4 + e] = 1.0f + __builtin_amdgcn_exp2f(fminf(__builtin_fmaf(acc[ai][bj][m][1][e], nrs, bg[4 + e]), 86.f));
;                         }
;                         gst<u32x4>(p0 + (ai * HALF + m * 16) * 3072, pack8(v));
;                         asm volatile("" ::: "memory");
;                     }
.LBB0_422:
	s_movk_i32 s9, 0x1800
	s_and_b64 vcc, exec, s[14:15]
	v_readlane_b32 s14, v254, 57
	s_lshl_b32 s60, s70, 7
	v_mad_i64_i32 v[132:133], s[16:17], v2, s9, 0
	v_readlane_b32 s15, v254, 58
	s_addk_i32 s60, 0xfa80
	v_lshlrev_b32_e32 v159, 2, v155
	v_lshl_add_u64 v[140:141], s[14:15], 0, v[132:133]
	s_cbranch_vccz .LBB0_432
	s_add_i32 s9, s8, 0xffffed00
	s_and_b64 s[14:15], s[10:11], exec
	s_cselect_b32 s14, s60, s9
	s_cselect_b32 s9, 0, 0x800
	s_lshl_b32 s26, s9, 1
	s_ashr_i32 s15, s14, 31
	s_lshl_b32 s9, s9, 2
	v_lshl_add_u64 v[132:133], v[140:141], 0, s[26:27]
	s_add_u32 s9, s62, s9
	v_lshl_add_u64 v[142:143], s[14:15], 1, v[132:133]
	s_addc_u32 s16, s63, 0
	s_lshl_b64 s[14:15], s[14:15], 2
	s_add_u32 s14, s9, s14
	s_addc_u32 s15, s16, s15
	global_load_dwordx4 v[132:135], v159, s[14:15] offset:16
	global_load_dwordx4 v[168:171], v159, s[14:15]
	v_lshlrev_b32_e32 v0, 1, v155
	v_lshl_add_u64 v[142:143], v[142:143], 0, v[0:1]
	ds_read_b32 v0, v154
	s_mov_b32 s9, 0x18000
	s_waitcnt lgkmcnt(0)
	v_mul_f32_e32 v0, 0xbfb8aa3b, v0
	s_waitcnt vmcnt(1)
	v_mul_f32_e32 v166, 0xbfb8aa3b, v132
	v_mul_f32_e32 v162, 0xbfb8aa3b, v134
	s_waitcnt vmcnt(0)
	v_mul_f32_e32 v165, 0xbfb8aa3b, v169
	v_mul_f32_e32 v164, 0xbfb8aa3b, v133
	v_fma_f32 v133, v112, v0, v166
	v_fma_f32 v169, v114, v0, v162
	v_mul_f32_e32 v167, 0xbfb8aa3b, v168
	v_mul_f32_e32 v163, 0xbfb8aa3b, v170
	v_mul_f32_e32 v161, 0xbfb8aa3b, v171
	v_mul_f32_e32 v160, 0xbfb8aa3b, v135
	v_min_f32_e32 v133, 0x42ac0000, v133
	v_min_f32_e32 v169, 0x42ac0000, v169
	v_fma_f32 v132, v120, v0, v167
	v_exp_f32_e32 v134, v133
	v_fma_f32 v133, v121, v0, v165
	v_fma_f32 v135, v113, v0, v164
	v_fma_f32 v168, v122, v0, v163
	v_exp_f32_e32 v170, v169
	v_fma_f32 v169, v123, v0, v161
	v_fma_f32 v0, v115, v0, v160
	v_min_f32_e32 v132, 0x42ac0000, v132
	v_min_f32_e32 v133, 0x42ac0000, v133
	v_min_f32_e32 v135, 0x42ac0000, v135
	v_min_f32_e32 v168, 0x42ac0000, v168
	v_min_f32_e32 v169, 0x42ac0000, v169
	v_min_f32_e32 v0, 0x42ac0000, v0
	v_exp_f32_e32 v132, v132
	v_exp_f32_e32 v133, v133
	v_exp_f32_e32 v135, v135
	v_exp_f32_e32 v168, v168
	v_exp_f32_e32 v169, v169
	v_exp_f32_e32 v171, v0
	v_pk_add_f32 v[132:133], v[132:133], 1.0 op_sel_hi:[1,0]
	v_pk_add_f32 v[134:135], v[134:135], 1.0 op_sel_hi:[1,0]
	v_pk_add_f32 v[168:169], v[168:169], 1.0 op_sel_hi:[1,0]
	v_pk_add_f32 v[170:171], v[170:171], 1.0 op_sel_hi:[1,0]
	v_cvt_pk_bf16_f32 v132, v132, v133
	v_cvt_pk_bf16_f32 v133, v168, v169
	v_cvt_pk_bf16_f32 v134, v134, v135
	v_cvt_pk_bf16_f32 v135, v170, v171
	global_store_dwordx4 v[142:143], v[132:135], off sc1
	ds_read_b32 v0, v154 offset:64
	s_waitcnt lgkmcnt(0)
	v_mul_f32_e32 v0, 0xbfb8aa3b, v0
	v_fma_f32 v133, v88, v0, v166
	v_fma_f32 v169, v90, v0, v162
	v_min_f32_e32 v133, 0x42ac0000, v133
	v_min_f32_e32 v169, 0x42ac0000, v169
	v_fma_f32 v132, v100, v0, v167
	v_exp_f32_e32 v134, v133
	v_fma_f32 v133, v101, v0, v165
	v_fma_f32 v168, v102, v0, v163
	v_exp_f32_e32 v170, v169
	v_fma_f32 v169, v103, v0, v161
	v_min_f32_e32 v132, 0x42ac0000, v132
	v_min_f32_e32 v133, 0x42ac0000, v133
	v_fma_f32 v135, v89, v0, v164
	v_min_f32_e32 v168, 0x42ac0000, v168
	v_min_f32_e32 v169, 0x42ac0000, v169
	v_fma_f32 v0, v91, v0, v160
	v_exp_f32_e32 v132, v132
	v_exp_f32_e32 v133, v133
	v_min_f32_e32 v135, 0x42ac0000, v135
	v_exp_f32_e32 v168, v168
	v_exp_f32_e32 v169, v169
	v_min_f32_e32 v0, 0x42ac0000, v0
	v_exp_f32_e32 v135, v135
	v_exp_f32_e32 v171, v0
	v_pk_add_f32 v[132:133], v[132:133], 1.0 op_sel_hi:[1,0]
	v_pk_add_f32 v[168:169], v[168:169], 1.0 op_sel_hi:[1,0]
	v_pk_add_f32 v[134:135], v[134:135], 1.0 op_sel_hi:[1,0]
	v_pk_add_f32 v[170:171], v[170:171], 1.0 op_sel_hi:[1,0]
	v_cvt_pk_bf16_f32 v132, v132, v133
	v_cvt_pk_bf16_f32 v133, v168, v169
	v_add_co_u32_e32 v168, vcc, s9, v142
	v_cvt_pk_bf16_f32 v134, v134, v135
	v_cvt_pk_bf16_f32 v135, v170, v171
	v_addc_co_u32_e32 v169, vcc, 0, v143, vcc
	global_store_dwordx4 v[168:169], v[132:135], off sc1
	ds_read_b32 v0, v154 offset:128
	s_mov_b32 s9, 0x30000
	s_waitcnt lgkmcnt(0)
	v_mul_f32_e32 v0, 0xbfb8aa3b, v0
	v_fma_f32 v133, v56, v0, v166
	v_fma_f32 v169, v58, v0, v162
	v_min_f32_e32 v133, 0x42ac0000, v133
	v_min_f32_e32 v169, 0x42ac0000, v169
	v_fma_f32 v132, v68, v0, v167
	v_exp_f32_e32 v134, v133
	v_fma_f32 v133, v69, v0, v165
	v_fma_f32 v168, v70, v0, v163
	v_exp_f32_e32 v170, v169
	v_fma_f32 v169, v71, v0, v161
	v_min_f32_e32 v132, 0x42ac0000, v132
	v_min_f32_e32 v133, 0x42ac0000, v133
	v_fma_f32 v135, v57, v0, v164
	v_min_f32_e32 v168, 0x42ac0000, v168
	v_min_f32_e32 v169, 0x42ac0000, v169
	v_fma_f32 v0, v59, v0, v160
	v_exp_f32_e32 v132, v132
	v_exp_f32_e32 v133, v133
	v_min_f32_e32 v135, 0x42ac0000, v135
	v_exp_f32_e32 v168, v168
	v_exp_f32_e32 v169, v169
	v_min_f32_e32 v0, 0x42ac0000, v0
	v_exp_f32_e32 v135, v135
	v_exp_f32_e32 v171, v0
	v_pk_add_f32 v[132:133], v[132:133], 1.0 op_sel_hi:[1,0]
	v_pk_add_f32 v[168:169], v[168:169], 1.0 op_sel_hi:[1,0]
	v_pk_add_f32 v[134:135], v[134:135], 1.0 op_sel_hi:[1,0]
	v_pk_add_f32 v[170:171], v[170:171], 1.0 op_sel_hi:[1,0]
	v_cvt_pk_bf16_f32 v132, v132, v133
	v_cvt_pk_bf16_f32 v133, v168, v169
	v_add_co_u32_e32 v168, vcc, s9, v142
	v_cvt_pk_bf16_f32 v134, v134, v135
	v_cvt_pk_bf16_f32 v135, v170, v171
	v_addc_co_u32_e32 v169, vcc, 0, v143, vcc
	global_store_dwordx4 v[168:169], v[132:135], off sc1
	ds_read_b32 v0, v154 offset:192
	s_mov_b32 s9, 0x48000
	s_waitcnt lgkmcnt(0)
; __device__ __forceinline__ u32x4 pack8(const float (&v)[8]) { u32x4 w; w.x = pk2(v[0], v[1]); w.y = pk2(v[2], v[3]); w.z = pk2(v[4], v[5]); w.w = pk2(v[6], v[7]); return w; }
;     __device__ __forceinline__ bool operator()(Acc& acc, const Unit& u, int wr, int wc, int fr, int fq, const LAS float* rstab) const {
;     ...
;                 for (int ai = 0; ai < 2; ++ai)
; #pragma unroll
;                     for (int m = 0; m < 4; ++m) {
;                         const float nrs = -LOG2E * rsp[ai * HALF + m * 16];
;                         float v[8];
; #pragma unroll
;                         for (int e = 0; e < 4; ++e) {
;                             v[e] = 1.0f + __builtin_amdgcn_exp2f(fminf(__builtin_fmaf(acc[ai][bj][m][0][e], nrs, bg[e]), 86.f));
;                             v[4 + e] = 1.0f + __builtin_amdgcn_exp2f(fminf(__builtin_fmaf(acc[ai][bj][m][1][e], nrs, bg[4 + e]), 86.f));
;                         }
;                         gst<u32x4>(p0 + (ai * HALF + m * 16) * 3072, pack8(v));
;                         asm volatile("" ::: "memory");
;                     }
	v_mul_f32_e32 v0, 0xbfb8aa3b, v0
	v_fma_f32 v133, v28, v0, v166
	v_fma_f32 v169, v30, v0, v162
	v_min_f32_e32 v133, 0x42ac0000, v133
	v_min_f32_e32 v169, 0x42ac0000, v169
	v_fma_f32 v132, v36, v0, v167
	v_exp_f32_e32 v134, v133
	v_fma_f32 v133, v37, v0, v165
	v_fma_f32 v168, v38, v0, v163
	v_exp_f32_e32 v170, v169
	v_fma_f32 v169, v39, v0, v161
	v_min_f32_e32 v132, 0x42ac0000, v132
	v_min_f32_e32 v133, 0x42ac0000, v133
	v_fma_f32 v135, v29, v0, v164
	v_min_f32_e32 v168, 0x42ac0000, v168
	v_min_f32_e32 v169, 0x42ac0000, v169
	v_fma_f32 v0, v31, v0, v160
	v_exp_f32_e32 v132, v132
	v_exp_f32_e32 v133, v133
	v_min_f32_e32 v135, 0x42ac0000, v135
	v_exp_f32_e32 v168, v168
	v_exp_f32_e32 v169, v169
	v_min_f32_e32 v0, 0x42ac0000, v0
	v_exp_f32_e32 v135, v135
	v_exp_f32_e32 v171, v0
	v_pk_add_f32 v[132:133], v[132:133], 1.0 op_sel_hi:[1,0]
	v_pk_add_f32 v[168:169], v[168:169], 1.0 op_sel_hi:[1,0]
	v_pk_add_f32 v[134:135], v[134:135], 1.0 op_sel_hi:[1,0]
	v_pk_add_f32 v[170:171], v[170:171], 1.0 op_sel_hi:[1,0]
	v_cvt_pk_bf16_f32 v132, v132, v133
	v_cvt_pk_bf16_f32 v133, v168, v169
	v_add_co_u32_e32 v168, vcc, s9, v142
	v_cvt_pk_bf16_f32 v134, v134, v135
	v_cvt_pk_bf16_f32 v135, v170, v171
	v_addc_co_u32_e32 v169, vcc, 0, v143, vcc
	global_store_dwordx4 v[168:169], v[132:135], off sc1
	ds_read_b32 v0, v154 offset:512
	s_mov_b32 s9, 0xc0000
	s_waitcnt lgkmcnt(0)
	v_mul_f32_e32 v0, 0xbfb8aa3b, v0
	v_fma_f32 v133, v60, v0, v166
	v_fma_f32 v169, v62, v0, v162
	v_min_f32_e32 v133, 0x42ac0000, v133
	v_min_f32_e32 v169, 0x42ac0000, v169
	v_fma_f32 v132, v72, v0, v167
	v_exp_f32_e32 v134, v133
	v_fma_f32 v133, v73, v0, v165
	v_fma_f32 v168, v74, v0, v163
	v_exp_f32_e32 v170, v169
	v_fma_f32 v169, v75, v0, v161
	v_min_f32_e32 v132, 0x42ac0000, v132
	v_min_f32_e32 v133, 0x42ac0000, v133
	v_fma_f32 v135, v61, v0, v164
	v_min_f32_e32 v168, 0x42ac0000, v168
	v_min_f32_e32 v169, 0x42ac0000, v169
	v_fma_f32 v0, v63, v0, v160
	v_exp_f32_e32 v132, v132
	v_exp_f32_e32 v133, v133
	v_min_f32_e32 v135, 0x42ac0000, v135
	v_exp_f32_e32 v168, v168
	v_exp_f32_e32 v169, v169
	v_min_f32_e32 v0, 0x42ac0000, v0
	v_exp_f32_e32 v135, v135
	v_exp_f32_e32 v171, v0
	v_pk_add_f32 v[132:133], v[132:133], 1.0 op_sel_hi:[1,0]
	v_pk_add_f32 v[168:169], v[168:169], 1.0 op_sel_hi:[1,0]
	v_pk_add_f32 v[134:135], v[134:135], 1.0 op_sel_hi:[1,0]
	v_pk_add_f32 v[170:171], v[170:171], 1.0 op_sel_hi:[1,0]
	v_cvt_pk_bf16_f32 v132, v132, v133
	v_cvt_pk_bf16_f32 v133, v168, v169
	v_add_co_u32_e32 v168, vcc, s9, v142
	v_cvt_pk_bf16_f32 v134, v134, v135
	v_cvt_pk_bf16_f32 v135, v170, v171
	v_addc_co_u32_e32 v169, vcc, 0, v143, vcc
	global_store_dwordx4 v[168:169], v[132:135], off sc1
	ds_read_b32 v0, v154 offset:576
	s_mov_b32 s9, 0xd8000
	s_waitcnt lgkmcnt(0)
	v_mul_f32_e32 v0, 0xbfb8aa3b, v0
	v_fma_f32 v133, v32, v0, v166
	v_fma_f32 v169, v34, v0, v162
	v_min_f32_e32 v133, 0x42ac0000, v133
	v_min_f32_e32 v169, 0x42ac0000, v169
	v_fma_f32 v132, v40, v0, v167
	v_exp_f32_e32 v134, v133
	v_fma_f32 v133, v41, v0, v165
	v_fma_f32 v168, v42, v0, v163
	v_exp_f32_e32 v170, v169
	v_fma_f32 v169, v43, v0, v161
	v_min_f32_e32 v132, 0x42ac0000, v132
	v_min_f32_e32 v133, 0x42ac0000, v133
	v_fma_f32 v135, v33, v0, v164
	v_min_f32_e32 v168, 0x42ac0000, v168
	v_min_f32_e32 v169, 0x42ac0000, v169
	v_fma_f32 v0, v35, v0, v160
	v_exp_f32_e32 v132, v132
	v_exp_f32_e32 v133, v133
	v_min_f32_e32 v135, 0x42ac0000, v135
	v_exp_f32_e32 v168, v168
	v_exp_f32_e32 v169, v169
	v_min_f32_e32 v0, 0x42ac0000, v0
	v_exp_f32_e32 v135, v135
	v_exp_f32_e32 v171, v0
	v_pk_add_f32 v[132:133], v[132:133], 1.0 op_sel_hi:[1,0]
	v_pk_add_f32 v[168:169], v[168:169], 1.0 op_sel_hi:[1,0]
	v_pk_add_f32 v[134:135], v[134:135], 1.0 op_sel_hi:[1,0]
	v_pk_add_f32 v[170:171], v[170:171], 1.0 op_sel_hi:[1,0]
	v_cvt_pk_bf16_f32 v132, v132, v133
	v_cvt_pk_bf16_f32 v133, v168, v169
	v_add_co_u32_e32 v168, vcc, s9, v142
	v_cvt_pk_bf16_f32 v134, v134, v135
	v_cvt_pk_bf16_f32 v135, v170, v171
	v_addc_co_u32_e32 v169, vcc, 0, v143, vcc
	global_store_dwordx4 v[168:169], v[132:135], off sc1
	ds_read_b32 v0, v154 offset:640
	s_mov_b32 s9, 0xf0000
	s_waitcnt lgkmcnt(0)
	v_mul_f32_e32 v0, 0xbfb8aa3b, v0
	v_fma_f32 v133, v12, v0, v166
	v_fma_f32 v169, v14, v0, v162
	v_min_f32_e32 v133, 0x42ac0000, v133
	v_min_f32_e32 v169, 0x42ac0000, v169
	v_fma_f32 v132, v16, v0, v167
	v_exp_f32_e32 v134, v133
	v_fma_f32 v133, v17, v0, v165
	v_fma_f32 v168, v18, v0, v163
	v_exp_f32_e32 v170, v169
	v_fma_f32 v169, v19, v0, v161
	v_min_f32_e32 v132, 0x42ac0000, v132
	v_min_f32_e32 v133, 0x42ac0000, v133
	v_fma_f32 v135, v13, v0, v164
	v_min_f32_e32 v168, 0x42ac0000, v168
	v_min_f32_e32 v169, 0x42ac0000, v169
	v_fma_f32 v0, v15, v0, v160
	v_exp_f32_e32 v132, v132
	v_exp_f32_e32 v133, v133
	v_min_f32_e32 v135, 0x42ac0000, v135
	v_exp_f32_e32 v168, v168
	v_exp_f32_e32 v169, v169
	v_min_f32_e32 v0, 0x42ac0000, v0
	v_exp_f32_e32 v135, v135
	v_exp_f32_e32 v171, v0
	v_pk_add_f32 v[132:133], v[132:133], 1.0 op_sel_hi:[1,0]
	v_pk_add_f32 v[168:169], v[168:169], 1.0 op_sel_hi:[1,0]
	v_pk_add_f32 v[134:135], v[134:135], 1.0 op_sel_hi:[1,0]
	v_pk_add_f32 v[170:171], v[170:171], 1.0 op_sel_hi:[1,0]
	v_cvt_pk_bf16_f32 v132, v132, v133
	v_cvt_pk_bf16_f32 v133, v168, v169
	v_add_co_u32_e32 v168, vcc, s9, v142
	v_cvt_pk_bf16_f32 v134, v134, v135
	v_cvt_pk_bf16_f32 v135, v170, v171
	v_addc_co_u32_e32 v169, vcc, 0, v143, vcc
	global_store_dwordx4 v[168:169], v[132:135], off sc1
	ds_read_b32 v0, v154 offset:704
	v_add_co_u32_e32 v142, vcc, 0x108000, v142
	s_waitcnt lgkmcnt(0)
	v_mul_f32_e32 v0, 0xbfb8aa3b, v0
	v_fmac_f32_e32 v166, v4, v0
	v_fmac_f32_e32 v167, v8, v0
	v_min_f32_e32 v133, 0x42ac0000, v166
	v_fmac_f32_e32 v165, v9, v0
	v_fmac_f32_e32 v164, v5, v0
	v_fmac_f32_e32 v163, v10, v0
	v_fmac_f32_e32 v162, v6, v0
	v_fmac_f32_e32 v161, v11, v0
	v_fmac_f32_e32 v160, v7, v0
	v_min_f32_e32 v132, 0x42ac0000, v167
	v_exp_f32_e32 v134, v133
	v_min_f32_e32 v133, 0x42ac0000, v165
	v_min_f32_e32 v135, 0x42ac0000, v164
	v_min_f32_e32 v163, 0x42ac0000, v163
	v_min_f32_e32 v162, 0x42ac0000, v162
	v_min_f32_e32 v161, 0x42ac0000, v161
	v_min_f32_e32 v0, 0x42ac0000, v160
	v_exp_f32_e32 v132, v132
	v_exp_f32_e32 v133, v133
	v_exp_f32_e32 v135, v135
	v_exp_f32_e32 v164, v163
	v_exp_f32_e32 v162, v162
	v_exp_f32_e32 v165, v161
	v_exp_f32_e32 v163, v0
	v_pk_add_f32 v[132:133], v[132:133], 1.0 op_sel_hi:[1,0]
	v_pk_add_f32 v[134:135], v[134:135], 1.0 op_sel_hi:[1,0]
	v_pk_add_f32 v[164:165], v[164:165], 1.0 op_sel_hi:[1,0]
	v_pk_add_f32 v[160:161], v[162:163], 1.0 op_sel_hi:[1,0]
	v_cvt_pk_bf16_f32 v132, v132, v133
	v_cvt_pk_bf16_f32 v133, v164, v165
	v_cvt_pk_bf16_f32 v134, v134, v135
	v_cvt_pk_bf16_f32 v135, v160, v161
	v_addc_co_u32_e32 v143, vcc, 0, v143, vcc
	global_store_dwordx4 v[142:143], v[132:135], off sc1
	s_or_b32 s9, s8, 0x80
	s_cmpk_gt_i32 s9, 0xaff
	s_mov_b64 s[14:15], -1
	s_cbranch_scc0 .LBB0_433
; __device__ __forceinline__ u32x4 pack8(const float (&v)[8]) { u32x4 w; w.x = pk2(v[0], v[1]); w.y = pk2(v[2], v[3]); w.z = pk2(v[4], v[5]); w.w = pk2(v[6], v[7]); return w; }
;     __device__ __forceinline__ bool operator()(Acc& acc, const Unit& u, int wr, int wc, int fr, int fq, const LAS float* rstab) const {
;     ...
;             if (colt >= C_G) {
;                 const int pl = (u.pn < 19) ? bj : 2, go = (u.pn < 19) ? (u.pn - 11) * HALF : colt - (C_G + 2048);
;                 bf16_t* p0 = Gt + (size_t)rowb * 3072 + pl * 1024 + go + cl;
;                 float bg[8];
;                 { const f32x4 b0 = gld<f32x4>(bgate + pl * 1024 + go + cl), b1 = gld<f32x4>(bgate + pl * 1024 + go + cl + 4);
; #pragma unroll
;                   for (int e = 0; e < 4; ++e) { bg[e] = -LOG2E * b0[e]; bg[4 + e] = -LOG2E * b1[e]; } }
; #pragma unroll
;                 for (int ai = 0; ai < 2; ++ai)
; #pragma unroll
;                     for (int m = 0; m < 4; ++m) {
;                         const float nrs = -LOG2E * rsp[ai * HALF + m * 16];
;                         float v[8];
; #pragma unroll
;                         for (int e = 0; e < 4; ++e) {
;                             v[e] = 1.0f + __builtin_amdgcn_exp2f(fminf(__builtin_fmaf(acc[ai][bj][m][0][e], nrs, bg[e]), 86.f));
;                             v[4 + e] = 1.0f + __builtin_amdgcn_exp2f(fminf(__builtin_fmaf(acc[ai][bj][m][1][e], nrs, bg[4 + e]), 86.f));
;                         }
;                         gst<u32x4>(p0 + (ai * HALF + m * 16) * 3072, pack8(v));
;                         asm volatile("" ::: "memory");
;                     }
.LBB0_424:
	s_and_b64 vcc, exec, s[14:15]
	s_cbranch_vccz .LBB0_426
	s_add_i32 s12, s8, 0xffffed80
	s_and_b64 s[8:9], s[10:11], exec
	s_movk_i32 s9, 0x800
	s_cselect_b32 s8, s60, s12
	s_cselect_b32 s10, 0x400, s9
	s_lshl_b32 s26, s10, 1
	s_ashr_i32 s9, s8, 31
	s_lshl_b32 s10, s10, 2
	v_lshl_add_u64 v[132:133], v[140:141], 0, s[26:27]
	s_add_u32 s10, s62, s10
	v_lshl_add_u64 v[160:161], s[8:9], 1, v[132:133]
	s_addc_u32 s11, s63, 0
	s_lshl_b64 s[8:9], s[8:9], 2
	s_add_u32 s8, s10, s8
	s_addc_u32 s9, s11, s9
	global_load_dwordx4 v[132:135], v159, s[8:9] offset:16
	global_load_dwordx4 v[136:139], v159, s[8:9]
	v_lshlrev_b32_e32 v0, 1, v155
	s_mov_b32 s8, 0x18000
	s_waitcnt vmcnt(1)
	v_mul_f32_e32 v156, 0xbfb8aa3b, v132
	s_waitcnt vmcnt(0)
	v_mul_f32_e32 v157, 0xbfb8aa3b, v136
	v_mul_f32_e32 v143, 0xbfb8aa3b, v137
	v_lshl_add_u64 v[136:137], v[160:161], 0, v[0:1]
	ds_read_b32 v0, v154
	v_mul_f32_e32 v140, 0xbfb8aa3b, v134
	v_mul_f32_e32 v142, 0xbfb8aa3b, v133
	v_mul_f32_e32 v141, 0xbfb8aa3b, v138
	v_mul_f32_e32 v139, 0xbfb8aa3b, v139
	s_waitcnt lgkmcnt(0)
	v_mul_f32_e32 v0, 0xbfb8aa3b, v0
	v_fma_f32 v133, v124, v0, v156
	v_fma_f32 v159, v126, v0, v140
	v_mul_f32_e32 v138, 0xbfb8aa3b, v135
	v_min_f32_e32 v133, 0x42ac0000, v133
	v_min_f32_e32 v159, 0x42ac0000, v159
	v_fma_f32 v132, v128, v0, v157
	v_exp_f32_e32 v134, v133
	v_fma_f32 v133, v129, v0, v143
	v_fma_f32 v135, v125, v0, v142
	v_fma_f32 v158, v130, v0, v141
	v_exp_f32_e32 v160, v159
	v_fma_f32 v159, v131, v0, v139
	v_fma_f32 v0, v127, v0, v138
	v_min_f32_e32 v132, 0x42ac0000, v132
	v_min_f32_e32 v133, 0x42ac0000, v133
	v_min_f32_e32 v135, 0x42ac0000, v135
	v_min_f32_e32 v158, 0x42ac0000, v158
	v_min_f32_e32 v159, 0x42ac0000, v159
	v_min_f32_e32 v0, 0x42ac0000, v0
	v_exp_f32_e32 v132, v132
	v_exp_f32_e32 v133, v133
	v_exp_f32_e32 v135, v135
	v_exp_f32_e32 v158, v158
	v_exp_f32_e32 v159, v159
	v_exp_f32_e32 v161, v0
	v_pk_add_f32 v[132:133], v[132:133], 1.0 op_sel_hi:[1,0]
	v_pk_add_f32 v[134:135], v[134:135], 1.0 op_sel_hi:[1,0]
	v_pk_add_f32 v[158:159], v[158:159], 1.0 op_sel_hi:[1,0]
	v_pk_add_f32 v[160:161], v[160:161], 1.0 op_sel_hi:[1,0]
	v_cvt_pk_bf16_f32 v132, v132, v133
	v_cvt_pk_bf16_f32 v133, v158, v159
	v_cvt_pk_bf16_f32 v134, v134, v135
	v_cvt_pk_bf16_f32 v135, v160, v161
	global_store_dwordx4 v[136:137], v[132:135], off sc1
	ds_read_b32 v0, v154 offset:64
	s_waitcnt lgkmcnt(0)
	v_mul_f32_e32 v0, 0xbfb8aa3b, v0
	v_fma_f32 v133, v108, v0, v156
	v_fma_f32 v159, v110, v0, v140
	v_min_f32_e32 v133, 0x42ac0000, v133
	v_min_f32_e32 v159, 0x42ac0000, v159
	v_fma_f32 v132, v116, v0, v157
	v_exp_f32_e32 v134, v133
	v_fma_f32 v133, v117, v0, v143
	v_fma_f32 v158, v118, v0, v141
	v_exp_f32_e32 v160, v159
	v_fma_f32 v159, v119, v0, v139
	v_min_f32_e32 v132, 0x42ac0000, v132
	v_min_f32_e32 v133, 0x42ac0000, v133
	v_fma_f32 v135, v109, v0, v142
	v_min_f32_e32 v158, 0x42ac0000, v158
	v_min_f32_e32 v159, 0x42ac0000, v159
	v_fma_f32 v0, v111, v0, v138
	v_exp_f32_e32 v132, v132
	v_exp_f32_e32 v133, v133
	v_min_f32_e32 v135, 0x42ac0000, v135
	v_exp_f32_e32 v158, v158
	v_exp_f32_e32 v159, v159
	v_min_f32_e32 v0, 0x42ac0000, v0
	v_exp_f32_e32 v135, v135
	v_exp_f32_e32 v161, v0
	v_pk_add_f32 v[132:133], v[132:133], 1.0 op_sel_hi:[1,0]
	v_pk_add_f32 v[158:159], v[158:159], 1.0 op_sel_hi:[1,0]
	v_pk_add_f32 v[134:135], v[134:135], 1.0 op_sel_hi:[1,0]
	v_pk_add_f32 v[160:161], v[160:161], 1.0 op_sel_hi:[1,0]
	v_cvt_pk_bf16_f32 v132, v132, v133
	v_cvt_pk_bf16_f32 v133, v158, v159
	v_add_co_u32_e32 v158, vcc, s8, v136
	v_cvt_pk_bf16_f32 v134, v134, v135
	v_cvt_pk_bf16_f32 v135, v160, v161
	v_addc_co_u32_e32 v159, vcc, 0, v137, vcc
	global_store_dwordx4 v[158:159], v[132:135], off sc1
	ds_read_b32 v0, v154 offset:128
	s_mov_b32 s8, 0x30000
	s_waitcnt lgkmcnt(0)
	v_mul_f32_e32 v0, 0xbfb8aa3b, v0
	v_fma_f32 v133, v80, v0, v156
	v_fma_f32 v159, v82, v0, v140
	v_min_f32_e32 v133, 0x42ac0000, v133
	v_min_f32_e32 v159, 0x42ac0000, v159
	v_fma_f32 v132, v92, v0, v157
	v_exp_f32_e32 v134, v133
	v_fma_f32 v133, v93, v0, v143
	v_fma_f32 v158, v94, v0, v141
	v_exp_f32_e32 v160, v159
	v_fma_f32 v159, v95, v0, v139
	v_min_f32_e32 v132, 0x42ac0000, v132
	v_min_f32_e32 v133, 0x42ac0000, v133
	v_fma_f32 v135, v81, v0, v142
	v_min_f32_e32 v158, 0x42ac0000, v158
	v_min_f32_e32 v159, 0x42ac0000, v159
	v_fma_f32 v0, v83, v0, v138
	v_exp_f32_e32 v132, v132
	v_exp_f32_e32 v133, v133
	v_min_f32_e32 v135, 0x42ac0000, v135
	v_exp_f32_e32 v158, v158
	v_exp_f32_e32 v159, v159
	v_min_f32_e32 v0, 0x42ac0000, v0
	v_exp_f32_e32 v135, v135
	v_exp_f32_e32 v161, v0
	v_pk_add_f32 v[132:133], v[132:133], 1.0 op_sel_hi:[1,0]
	v_pk_add_f32 v[158:159], v[158:159], 1.0 op_sel_hi:[1,0]
	v_pk_add_f32 v[134:135], v[134:135], 1.0 op_sel_hi:[1,0]
	v_pk_add_f32 v[160:161], v[160:161], 1.0 op_sel_hi:[1,0]
	v_cvt_pk_bf16_f32 v132, v132, v133
	v_cvt_pk_bf16_f32 v133, v158, v159
	v_add_co_u32_e32 v158, vcc, s8, v136
	v_cvt_pk_bf16_f32 v134, v134, v135
	v_cvt_pk_bf16_f32 v135, v160, v161
	v_addc_co_u32_e32 v159, vcc, 0, v137, vcc
	global_store_dwordx4 v[158:159], v[132:135], off sc1
	ds_read_b32 v0, v154 offset:192
	s_mov_b32 s8, 0x48000
	s_waitcnt lgkmcnt(0)
; __device__ __forceinline__ u32x4 pack8(const float (&v)[8]) { u32x4 w; w.x = pk2(v[0], v[1]); w.y = pk2(v[2], v[3]); w.z = pk2(v[4], v[5]); w.w = pk2(v[6], v[7]); return w; }
;     __device__ __forceinline__ bool operator()(Acc& acc, const Unit& u, int wr, int wc, int fr, int fq, const LAS float* rstab) const {
;     ...
;                 for (int ai = 0; ai < 2; ++ai)
; #pragma unroll
;                     for (int m = 0; m < 4; ++m) {
;                         const float nrs = -LOG2E * rsp[ai * HALF + m * 16];
;                         float v[8];
; #pragma unroll
;                         for (int e = 0; e < 4; ++e) {
;                             v[e] = 1.0f + __builtin_amdgcn_exp2f(fminf(__builtin_fmaf(acc[ai][bj][m][0][e], nrs, bg[e]), 86.f));
;                             v[4 + e] = 1.0f + __builtin_amdgcn_exp2f(fminf(__builtin_fmaf(acc[ai][bj][m][1][e], nrs, bg[4 + e]), 86.f));
;                         }
;                         gst<u32x4>(p0 + (ai * HALF + m * 16) * 3072, pack8(v));
;                         asm volatile("" ::: "memory");
;                     }
	v_mul_f32_e32 v0, 0xbfb8aa3b, v0
	v_fma_f32 v133, v48, v0, v156
	v_fma_f32 v159, v50, v0, v140
	v_min_f32_e32 v133, 0x42ac0000, v133
	v_min_f32_e32 v159, 0x42ac0000, v159
	v_fma_f32 v132, v64, v0, v157
	v_exp_f32_e32 v134, v133
	v_fma_f32 v133, v65, v0, v143
	v_fma_f32 v158, v66, v0, v141
	v_exp_f32_e32 v160, v159
	v_fma_f32 v159, v67, v0, v139
	v_min_f32_e32 v132, 0x42ac0000, v132
	v_min_f32_e32 v133, 0x42ac0000, v133
	v_fma_f32 v135, v49, v0, v142
	v_min_f32_e32 v158, 0x42ac0000, v158
	v_min_f32_e32 v159, 0x42ac0000, v159
	v_fma_f32 v0, v51, v0, v138
	v_exp_f32_e32 v132, v132
	v_exp_f32_e32 v133, v133
	v_min_f32_e32 v135, 0x42ac0000, v135
	v_exp_f32_e32 v158, v158
	v_exp_f32_e32 v159, v159
	v_min_f32_e32 v0, 0x42ac0000, v0
	v_exp_f32_e32 v135, v135
	v_exp_f32_e32 v161, v0
	v_pk_add_f32 v[132:133], v[132:133], 1.0 op_sel_hi:[1,0]
	v_pk_add_f32 v[158:159], v[158:159], 1.0 op_sel_hi:[1,0]
	v_pk_add_f32 v[134:135], v[134:135], 1.0 op_sel_hi:[1,0]
	v_pk_add_f32 v[160:161], v[160:161], 1.0 op_sel_hi:[1,0]
	v_cvt_pk_bf16_f32 v132, v132, v133
	v_cvt_pk_bf16_f32 v133, v158, v159
	v_add_co_u32_e32 v158, vcc, s8, v136
	v_cvt_pk_bf16_f32 v134, v134, v135
	v_cvt_pk_bf16_f32 v135, v160, v161
	v_addc_co_u32_e32 v159, vcc, 0, v137, vcc
	global_store_dwordx4 v[158:159], v[132:135], off sc1
	ds_read_b32 v0, v154 offset:512
	s_mov_b32 s8, 0xc0000
	s_waitcnt lgkmcnt(0)
	v_mul_f32_e32 v0, 0xbfb8aa3b, v0
	v_fma_f32 v133, v104, v0, v156
	v_fma_f32 v159, v106, v0, v140
	v_min_f32_e32 v133, 0x42ac0000, v133
	v_min_f32_e32 v159, 0x42ac0000, v159
	v_fma_f32 v132, v96, v0, v157
	v_exp_f32_e32 v134, v133
	v_fma_f32 v133, v97, v0, v143
	v_fma_f32 v158, v98, v0, v141
	v_exp_f32_e32 v160, v159
	v_fma_f32 v159, v99, v0, v139
	v_min_f32_e32 v132, 0x42ac0000, v132
	v_min_f32_e32 v133, 0x42ac0000, v133
	v_fma_f32 v135, v105, v0, v142
	v_min_f32_e32 v158, 0x42ac0000, v158
	v_min_f32_e32 v159, 0x42ac0000, v159
	v_fma_f32 v0, v107, v0, v138
	v_exp_f32_e32 v132, v132
	v_exp_f32_e32 v133, v133
	v_min_f32_e32 v135, 0x42ac0000, v135
	v_exp_f32_e32 v158, v158
	v_exp_f32_e32 v159, v159
	v_min_f32_e32 v0, 0x42ac0000, v0
	v_exp_f32_e32 v135, v135
	v_exp_f32_e32 v161, v0
	v_pk_add_f32 v[132:133], v[132:133], 1.0 op_sel_hi:[1,0]
	v_pk_add_f32 v[158:159], v[158:159], 1.0 op_sel_hi:[1,0]
	v_pk_add_f32 v[134:135], v[134:135], 1.0 op_sel_hi:[1,0]
	v_pk_add_f32 v[160:161], v[160:161], 1.0 op_sel_hi:[1,0]
	v_cvt_pk_bf16_f32 v132, v132, v133
	v_cvt_pk_bf16_f32 v133, v158, v159
	v_add_co_u32_e32 v158, vcc, s8, v136
	v_cvt_pk_bf16_f32 v134, v134, v135
	v_cvt_pk_bf16_f32 v135, v160, v161
	v_addc_co_u32_e32 v159, vcc, 0, v137, vcc
	global_store_dwordx4 v[158:159], v[132:135], off sc1
	ds_read_b32 v0, v154 offset:576
	s_mov_b32 s8, 0xd8000
	s_waitcnt lgkmcnt(0)
	v_mul_f32_e32 v0, 0xbfb8aa3b, v0
	v_fma_f32 v133, v76, v0, v156
	v_fma_f32 v159, v78, v0, v140
	v_min_f32_e32 v133, 0x42ac0000, v133
	v_min_f32_e32 v159, 0x42ac0000, v159
	v_fma_f32 v132, v84, v0, v157
	v_exp_f32_e32 v134, v133
	v_fma_f32 v133, v85, v0, v143
	v_fma_f32 v158, v86, v0, v141
	v_exp_f32_e32 v160, v159
	v_fma_f32 v159, v87, v0, v139
	v_min_f32_e32 v132, 0x42ac0000, v132
	v_min_f32_e32 v133, 0x42ac0000, v133
	v_fma_f32 v135, v77, v0, v142
	v_min_f32_e32 v158, 0x42ac0000, v158
	v_min_f32_e32 v159, 0x42ac0000, v159
	v_fma_f32 v0, v79, v0, v138
	v_exp_f32_e32 v132, v132
	v_exp_f32_e32 v133, v133
	v_min_f32_e32 v135, 0x42ac0000, v135
	v_exp_f32_e32 v158, v158
	v_exp_f32_e32 v159, v159
	v_min_f32_e32 v0, 0x42ac0000, v0
	v_exp_f32_e32 v135, v135
	v_exp_f32_e32 v161, v0
	v_pk_add_f32 v[132:133], v[132:133], 1.0 op_sel_hi:[1,0]
	v_pk_add_f32 v[158:159], v[158:159], 1.0 op_sel_hi:[1,0]
	v_pk_add_f32 v[134:135], v[134:135], 1.0 op_sel_hi:[1,0]
	v_pk_add_f32 v[160:161], v[160:161], 1.0 op_sel_hi:[1,0]
	v_cvt_pk_bf16_f32 v132, v132, v133
	v_cvt_pk_bf16_f32 v133, v158, v159
	v_add_co_u32_e32 v158, vcc, s8, v136
	v_cvt_pk_bf16_f32 v134, v134, v135
	v_cvt_pk_bf16_f32 v135, v160, v161
	v_addc_co_u32_e32 v159, vcc, 0, v137, vcc
	global_store_dwordx4 v[158:159], v[132:135], off sc1
	ds_read_b32 v0, v154 offset:640
	s_mov_b32 s8, 0xf0000
	s_waitcnt lgkmcnt(0)
	v_mul_f32_e32 v0, 0xbfb8aa3b, v0
	v_fma_f32 v133, v44, v0, v156
	v_fma_f32 v159, v46, v0, v140
	v_min_f32_e32 v133, 0x42ac0000, v133
	v_min_f32_e32 v159, 0x42ac0000, v159
	v_fma_f32 v132, v52, v0, v157
	v_exp_f32_e32 v134, v133
	v_fma_f32 v133, v53, v0, v143
	v_fma_f32 v158, v54, v0, v141
	v_exp_f32_e32 v160, v159
	v_fma_f32 v159, v55, v0, v139
	v_min_f32_e32 v132, 0x42ac0000, v132
	v_min_f32_e32 v133, 0x42ac0000, v133
	v_fma_f32 v135, v45, v0, v142
	v_min_f32_e32 v158, 0x42ac0000, v158
	v_min_f32_e32 v159, 0x42ac0000, v159
	v_fma_f32 v0, v47, v0, v138
	v_exp_f32_e32 v132, v132
	v_exp_f32_e32 v133, v133
	v_min_f32_e32 v135, 0x42ac0000, v135
	v_exp_f32_e32 v158, v158
	v_exp_f32_e32 v159, v159
	v_min_f32_e32 v0, 0x42ac0000, v0
	v_exp_f32_e32 v135, v135
	v_exp_f32_e32 v161, v0
	v_pk_add_f32 v[132:133], v[132:133], 1.0 op_sel_hi:[1,0]
	v_pk_add_f32 v[158:159], v[158:159], 1.0 op_sel_hi:[1,0]
	v_pk_add_f32 v[134:135], v[134:135], 1.0 op_sel_hi:[1,0]
	v_pk_add_f32 v[160:161], v[160:161], 1.0 op_sel_hi:[1,0]
	v_cvt_pk_bf16_f32 v132, v132, v133
	v_cvt_pk_bf16_f32 v133, v158, v159
	v_add_co_u32_e32 v158, vcc, s8, v136
	v_cvt_pk_bf16_f32 v134, v134, v135
	v_cvt_pk_bf16_f32 v135, v160, v161
	v_addc_co_u32_e32 v159, vcc, 0, v137, vcc
	global_store_dwordx4 v[158:159], v[132:135], off sc1
	ds_read_b32 v0, v154 offset:704
	v_add_co_u32_e32 v136, vcc, 0x108000, v136
	s_waitcnt lgkmcnt(0)
	v_mul_f32_e32 v0, 0xbfb8aa3b, v0
	v_fmac_f32_e32 v156, v20, v0
	v_fmac_f32_e32 v157, v24, v0
	v_min_f32_e32 v133, 0x42ac0000, v156
	v_fmac_f32_e32 v143, v25, v0
	v_fmac_f32_e32 v142, v21, v0
	v_fmac_f32_e32 v141, v26, v0
	v_fmac_f32_e32 v140, v22, v0
	v_fmac_f32_e32 v139, v27, v0
	v_fmac_f32_e32 v138, v23, v0
	v_min_f32_e32 v132, 0x42ac0000, v157
	v_exp_f32_e32 v134, v133
	v_min_f32_e32 v133, 0x42ac0000, v143
	v_min_f32_e32 v135, 0x42ac0000, v142
	v_min_f32_e32 v141, 0x42ac0000, v141
	v_min_f32_e32 v140, 0x42ac0000, v140
	v_min_f32_e32 v139, 0x42ac0000, v139
	v_min_f32_e32 v0, 0x42ac0000, v138
	v_exp_f32_e32 v132, v132
	v_exp_f32_e32 v133, v133
	v_exp_f32_e32 v135, v135
	v_exp_f32_e32 v142, v141
	v_exp_f32_e32 v140, v140
	v_exp_f32_e32 v143, v139
	v_exp_f32_e32 v141, v0
	v_pk_add_f32 v[132:133], v[132:133], 1.0 op_sel_hi:[1,0]
	v_pk_add_f32 v[134:135], v[134:135], 1.0 op_sel_hi:[1,0]
	v_pk_add_f32 v[142:143], v[142:143], 1.0 op_sel_hi:[1,0]
	v_pk_add_f32 v[138:139], v[140:141], 1.0 op_sel_hi:[1,0]
	v_cvt_pk_bf16_f32 v132, v132, v133
	v_cvt_pk_bf16_f32 v133, v142, v143
	v_cvt_pk_bf16_f32 v134, v134, v135
	v_cvt_pk_bf16_f32 v135, v138, v139
	v_addc_co_u32_e32 v137, vcc, 0, v137, vcc
	global_store_dwordx4 v[136:137], v[132:135], off sc1
